# adds: EpiLn stage-4 gamma/beta for both halves loaded together (no wait on first-half stores); P10 skinny sample GEMM 30-deep load ring; sample-attention K pass first load no longer waited alone
# baseline (speedup 1.0000x reference)
; __device__ __forceinline__ float rowsum16(float v) { v += dppf<0xB1>(v); v += dppf<0x4E>(v); v += dppf<0x141>(v); v += dppf<0x140>(v); return v; }
; __device__ __forceinline__ void attn_sample_unit(const Params& p, int unit, float* lds) {
;     ...
;             float4 kv[17];
; #pragma unroll
;             for (int i = 0; i < 17; ++i) {
;                 const int j = (ob * 17 + i) * 4 + ks, jc = j > 128 ? 128 : j;
;                 const int pos = 2048 + wave - (jc << dsh);
;                 const float* kp = (pos < 2048) ? kc + (size_t)pos * 1024 : kn + (size_t)(pos - 2048) * 1024;
;                 kv[i] = *(const float4*)kp;
;             }
;             float pr[17];
; #pragma unroll
;             for (int i = 0; i < 17; ++i) pr[i] = rowsum16(q0 * kv[i].x + q1 * kv[i].y + q2 * kv[i].z + q3 * kv[i].w);
.LBB0_350:
	v_or_b32_e32 v0, s16, v175
	v_lshlrev_b32_e32 v1, s23, v0
	v_sub_u32_e32 v2, v111, v1
	v_subrev_co_u32_e32 v3, vcc, 0x800, v2
	s_nop 1
	v_cndmask_b32_e32 v68, v3, v2, vcc
	v_cndmask_b32_e32 v3, v101, v97, vcc
	v_cndmask_b32_e32 v2, v100, v96, vcc
	v_lshlrev_b64 v[4:5], 12, v[68:69]
	v_lshl_add_u64 v[2:3], v[2:3], 0, v[4:5]
	global_load_dwordx4 v[18:21], v[2:3], off
	v_add_u32_e32 v2, s16, v132
	v_lshlrev_b32_e32 v2, s23, v2
	v_sub_u32_e32 v3, v111, v2
	v_subrev_co_u32_e32 v4, vcc, s3, v3
	s_nop 0
	s_nop 0
	v_cndmask_b32_e32 v68, v4, v3, vcc
	v_cndmask_b32_e32 v5, v101, v97, vcc
	v_cndmask_b32_e32 v4, v100, v96, vcc
	v_lshlrev_b64 v[6:7], 12, v[68:69]
	v_or_b32_e32 v3, 8, v0
	v_lshl_add_u64 v[4:5], v[4:5], 0, v[6:7]
	v_lshlrev_b32_e32 v3, s23, v3
	global_load_dwordx4 v[22:25], v[4:5], off
	v_sub_u32_e32 v4, v111, v3
	v_subrev_co_u32_e32 v5, vcc, s3, v4
	s_nop 0
	s_nop 0
	v_cndmask_b32_e32 v68, v5, v4, vcc
	v_cndmask_b32_e32 v5, v101, v97, vcc
	v_cndmask_b32_e32 v4, v100, v96, vcc
	v_lshlrev_b64 v[6:7], 12, v[68:69]
	v_lshl_add_u64 v[4:5], v[4:5], 0, v[6:7]
	global_load_dwordx4 v[26:29], v[4:5], off
	v_add_u32_e32 v4, s16, v133
	v_lshlrev_b32_e32 v4, s23, v4
	v_sub_u32_e32 v5, v111, v4
	v_subrev_co_u32_e32 v6, vcc, s3, v5
	s_nop 0
	s_nop 0
	v_cndmask_b32_e32 v68, v6, v5, vcc
	v_cndmask_b32_e32 v7, v101, v97, vcc
	v_cndmask_b32_e32 v6, v100, v96, vcc
	v_lshlrev_b64 v[8:9], 12, v[68:69]
	v_or_b32_e32 v5, 16, v0
	v_lshl_add_u64 v[6:7], v[6:7], 0, v[8:9]
	v_lshlrev_b32_e32 v5, s23, v5
	global_load_dwordx4 v[30:33], v[6:7], off
	v_sub_u32_e32 v6, v111, v5
	v_lshlrev_b32_e32 v68, 12, v6
	v_add_u32_e32 v6, s16, v134
	v_lshlrev_b32_e32 v6, s23, v6
	v_sub_u32_e32 v7, v111, v6
	v_lshl_add_u64 v[8:9], v[96:97], 0, v[68:69]
	v_lshlrev_b32_e32 v68, 12, v7
	v_or_b32_e32 v7, 24, v0
	v_lshlrev_b32_e32 v7, s23, v7
	v_lshl_add_u64 v[10:11], v[96:97], 0, v[68:69]
	global_load_dwordx4 v[34:37], v[8:9], off
	global_load_dwordx4 v[38:41], v[10:11], off
	v_sub_u32_e32 v8, v111, v7
	v_lshlrev_b32_e32 v68, 12, v8
	v_add_u32_e32 v8, s16, v135
	v_lshlrev_b32_e32 v8, s23, v8
	v_sub_u32_e32 v9, v111, v8
	v_lshl_add_u64 v[10:11], v[96:97], 0, v[68:69]
	v_lshlrev_b32_e32 v68, 12, v9
	v_lshl_add_u64 v[12:13], v[96:97], 0, v[68:69]
	global_load_dwordx4 v[42:45], v[10:11], off
	global_load_dwordx4 v[46:49], v[12:13], off
	v_or_b32_e32 v9, 32, v0
	v_lshlrev_b32_e32 v9, s23, v9
	v_sub_u32_e32 v10, v111, v9
	v_lshlrev_b32_e32 v68, 12, v10
	v_add_u32_e32 v10, s16, v136
	v_lshlrev_b32_e32 v10, s23, v10
	v_sub_u32_e32 v11, v111, v10
	v_lshl_add_u64 v[12:13], v[96:97], 0, v[68:69]
	v_lshlrev_b32_e32 v68, 12, v11
	v_lshl_add_u64 v[14:15], v[96:97], 0, v[68:69]
	global_load_dwordx4 v[50:53], v[12:13], off
	global_load_dwordx4 v[54:57], v[14:15], off
	v_or_b32_e32 v11, 40, v0
	v_lshlrev_b32_e32 v12, s23, v11
	v_sub_u32_e32 v11, v111, v12
	v_lshlrev_b32_e32 v68, 12, v11
	v_add_u32_e32 v11, s16, v137
	v_lshlrev_b32_e32 v13, s23, v11
	v_sub_u32_e32 v11, v111, v13
	v_lshl_add_u64 v[14:15], v[96:97], 0, v[68:69]
	v_lshlrev_b32_e32 v68, 12, v11
	v_lshl_add_u64 v[16:17], v[96:97], 0, v[68:69]
	global_load_dwordx4 v[58:61], v[14:15], off
	global_load_dwordx4 v[62:65], v[16:17], off
	v_or_b32_e32 v11, 48, v0
	v_lshlrev_b32_e32 v15, s23, v11
	v_sub_u32_e32 v11, v111, v15
	v_lshlrev_b32_e32 v68, 12, v11
	v_add_u32_e32 v11, s16, v138
	v_lshlrev_b32_e32 v16, s23, v11
	v_sub_u32_e32 v11, v111, v16
	v_lshl_add_u64 v[66:67], v[96:97], 0, v[68:69]
	v_lshlrev_b32_e32 v68, 12, v11
	v_lshl_add_u64 v[108:109], v[96:97], 0, v[68:69]
	global_load_dwordx4 v[104:107], v[66:67], off
	global_load_dwordx4 v[114:117], v[108:109], off
	v_or_b32_e32 v11, 56, v0
	v_lshlrev_b32_e32 v17, s23, v11
	v_sub_u32_e32 v11, v111, v17
	v_add_u32_e32 v14, s16, v139
	v_lshlrev_b32_e32 v68, 12, v11
	v_min_u32_e32 v11, 0x80, v14
	v_lshlrev_b32_e32 v11, s23, v11
	v_sub_u32_e32 v11, v111, v11
	v_lshl_add_u64 v[66:67], v[96:97], 0, v[68:69]
	v_lshlrev_b32_e32 v68, 12, v11
	v_lshl_add_u64 v[108:109], v[96:97], 0, v[68:69]
	global_load_dwordx4 v[118:121], v[66:67], off
	global_load_dwordx4 v[122:125], v[108:109], off
	v_add_u32_e32 v11, s16, v140
	v_min_u32_e32 v66, 0x80, v11
	v_lshlrev_b32_e32 v66, s23, v66
	v_sub_u32_e32 v66, v111, v66
	v_lshlrev_b32_e32 v68, 12, v66
	v_lshl_add_u64 v[66:67], v[96:97], 0, v[68:69]
	global_load_dwordx4 v[146:149], v[66:67], off
	s_waitcnt vmcnt(15)
	v_mul_f32_e32 v19, v143, v19
	v_fmac_f32_e32 v19, v142, v18
	v_fmac_f32_e32 v19, v144, v20
	v_mul_f32_e32 v20, v143, v23
	v_fmac_f32_e32 v20, v142, v22
	v_fmac_f32_e32 v20, v144, v24
	s_waitcnt vmcnt(14)
	v_mul_f32_e32 v22, v143, v27
	v_fmac_f32_e32 v22, v142, v26
	v_fmac_f32_e32 v22, v144, v28
	v_fmac_f32_e32 v19, v145, v21
	s_waitcnt vmcnt(13)
	v_mul_f32_e32 v24, v143, v31
	v_fmac_f32_e32 v24, v142, v30
	v_fmac_f32_e32 v24, v144, v32
	v_fmac_f32_e32 v20, v145, v25
	v_fmac_f32_e32 v22, v145, v29
	v_fmac_f32_e32 v24, v145, v33
	v_add_f32_dpp v18, v19, v19 quad_perm:[1,0,3,2] row_mask:0xf bank_mask:0xf bound_ctrl:1
	v_add_f32_dpp v20, v20, v20 quad_perm:[1,0,3,2] row_mask:0xf bank_mask:0xf bound_ctrl:1
	v_add_f32_dpp v22, v22, v22 quad_perm:[1,0,3,2] row_mask:0xf bank_mask:0xf bound_ctrl:1
	v_add_f32_dpp v24, v24, v24 quad_perm:[1,0,3,2] row_mask:0xf bank_mask:0xf bound_ctrl:1
	s_waitcnt vmcnt(12)
	v_mul_f32_e32 v26, v143, v35
	v_fmac_f32_e32 v26, v142, v34
	v_fmac_f32_e32 v26, v144, v36
	s_waitcnt vmcnt(11)
	v_mul_f32_e32 v28, v143, v39
	v_fmac_f32_e32 v28, v142, v38
	v_fmac_f32_e32 v28, v144, v40
	v_fmac_f32_e32 v28, v145, v41
	v_fmac_f32_e32 v26, v145, v37
	v_add_f32_dpp v18, v18, v18 quad_perm:[2,3,0,1] row_mask:0xf bank_mask:0xf bound_ctrl:1
	s_waitcnt vmcnt(10)
; template <int CTRL> __device__ __forceinline__ float dppf(float v) { return __int_as_float(__builtin_amdgcn_update_dpp(0, __float_as_int(v), CTRL, 0xf, 0xf, false)); }
; __device__ __forceinline__ float rowsum16(float v) { v += dppf<0xB1>(v); v += dppf<0x4E>(v); v += dppf<0x141>(v); v += dppf<0x140>(v); return v; }
; __device__ __forceinline__ void attn_sample_unit(const Params& p, int unit, float* lds) {
;     ...
;             float pr[17];
; #pragma unroll
;             for (int i = 0; i < 17; ++i) pr[i] = rowsum16(q0 * kv[i].x + q1 * kv[i].y + q2 * kv[i].z + q3 * kv[i].w);
	v_mul_f32_e32 v30, v143, v43
	s_waitcnt vmcnt(9)
	v_mul_f32_e32 v32, v143, v47
	v_fmac_f32_e32 v32, v142, v46
	v_fmac_f32_e32 v32, v144, v48
	v_fmac_f32_e32 v32, v145, v49
	v_fmac_f32_e32 v30, v142, v42
	v_fmac_f32_e32 v30, v144, v44
	v_add_f32_dpp v32, v32, v32 quad_perm:[1,0,3,2] row_mask:0xf bank_mask:0xf bound_ctrl:1
	v_fmac_f32_e32 v30, v145, v45
	v_add_f32_dpp v26, v26, v26 quad_perm:[1,0,3,2] row_mask:0xf bank_mask:0xf bound_ctrl:1
	v_add_f32_dpp v32, v32, v32 quad_perm:[2,3,0,1] row_mask:0xf bank_mask:0xf bound_ctrl:1
	v_add_f32_dpp v28, v28, v28 quad_perm:[1,0,3,2] row_mask:0xf bank_mask:0xf bound_ctrl:1
	v_add_f32_dpp v30, v30, v30 quad_perm:[1,0,3,2] row_mask:0xf bank_mask:0xf bound_ctrl:1
	v_add_f32_dpp v36, v32, v32 row_half_mirror row_mask:0xf bank_mask:0xf bound_ctrl:1
	s_waitcnt vmcnt(8)
	v_mul_f32_e32 v32, v143, v51
	v_fmac_f32_e32 v32, v142, v50
	v_fmac_f32_e32 v32, v144, v52
	v_fmac_f32_e32 v32, v145, v53
	v_add_f32_dpp v20, v20, v20 quad_perm:[2,3,0,1] row_mask:0xf bank_mask:0xf bound_ctrl:1
	v_add_f32_dpp v22, v22, v22 quad_perm:[2,3,0,1] row_mask:0xf bank_mask:0xf bound_ctrl:1
	v_add_f32_dpp v32, v32, v32 quad_perm:[1,0,3,2] row_mask:0xf bank_mask:0xf bound_ctrl:1
	v_add_f32_dpp v24, v24, v24 quad_perm:[2,3,0,1] row_mask:0xf bank_mask:0xf bound_ctrl:1
	v_add_f32_dpp v26, v26, v26 quad_perm:[2,3,0,1] row_mask:0xf bank_mask:0xf bound_ctrl:1
	v_add_f32_dpp v32, v32, v32 quad_perm:[2,3,0,1] row_mask:0xf bank_mask:0xf bound_ctrl:1
	v_add_f32_dpp v28, v28, v28 quad_perm:[2,3,0,1] row_mask:0xf bank_mask:0xf bound_ctrl:1
	v_add_f32_dpp v30, v30, v30 quad_perm:[2,3,0,1] row_mask:0xf bank_mask:0xf bound_ctrl:1
	v_add_f32_dpp v39, v32, v32 row_half_mirror row_mask:0xf bank_mask:0xf bound_ctrl:1
	s_waitcnt vmcnt(7)
	v_mul_f32_e32 v32, v143, v55
	v_fmac_f32_e32 v32, v142, v54
	v_fmac_f32_e32 v32, v144, v56
	v_fmac_f32_e32 v32, v145, v57
	v_add_f32_dpp v18, v18, v18 row_half_mirror row_mask:0xf bank_mask:0xf bound_ctrl:1
	v_mov_b32_e32 v19, 0
	v_add_f32_dpp v32, v32, v32 quad_perm:[1,0,3,2] row_mask:0xf bank_mask:0xf bound_ctrl:1
	v_add_f32_dpp v20, v20, v20 row_half_mirror row_mask:0xf bank_mask:0xf bound_ctrl:1
	v_mov_b32_e32 v21, 0
	v_add_f32_dpp v32, v32, v32 quad_perm:[2,3,0,1] row_mask:0xf bank_mask:0xf bound_ctrl:1
	v_add_f32_dpp v22, v22, v22 row_half_mirror row_mask:0xf bank_mask:0xf bound_ctrl:1
	v_mov_b32_e32 v23, 0
	v_add_f32_dpp v41, v32, v32 row_half_mirror row_mask:0xf bank_mask:0xf bound_ctrl:1
	s_waitcnt vmcnt(6)
	v_mul_f32_e32 v32, v143, v59
	v_fmac_f32_e32 v32, v142, v58
	v_fmac_f32_e32 v32, v144, v60
	v_fmac_f32_e32 v32, v145, v61
	v_add_f32_dpp v24, v24, v24 row_half_mirror row_mask:0xf bank_mask:0xf bound_ctrl:1
	v_mov_b32_e32 v25, 0
	v_add_f32_dpp v32, v32, v32 quad_perm:[1,0,3,2] row_mask:0xf bank_mask:0xf bound_ctrl:1
	v_add_f32_dpp v26, v26, v26 row_half_mirror row_mask:0xf bank_mask:0xf bound_ctrl:1
	v_mov_b32_e32 v27, 0
	v_add_f32_dpp v32, v32, v32 quad_perm:[2,3,0,1] row_mask:0xf bank_mask:0xf bound_ctrl:1
	v_add_f32_dpp v28, v28, v28 row_half_mirror row_mask:0xf bank_mask:0xf bound_ctrl:1
	v_mov_b32_e32 v29, 0
	v_add_f32_dpp v43, v32, v32 row_half_mirror row_mask:0xf bank_mask:0xf bound_ctrl:1
	s_waitcnt vmcnt(5)
	v_mul_f32_e32 v32, v143, v63
	v_fmac_f32_e32 v32, v142, v62
	v_fmac_f32_e32 v32, v144, v64
	v_fmac_f32_e32 v32, v145, v65
	v_add_f32_dpp v30, v30, v30 row_half_mirror row_mask:0xf bank_mask:0xf bound_ctrl:1
	v_mov_b32_e32 v31, 0
	v_add_f32_dpp v32, v32, v32 quad_perm:[1,0,3,2] row_mask:0xf bank_mask:0xf bound_ctrl:1
	v_mov_b32_e32 v38, 0
	v_mov_b32_e32 v40, 0
	v_add_f32_dpp v32, v32, v32 quad_perm:[2,3,0,1] row_mask:0xf bank_mask:0xf bound_ctrl:1
	v_mov_b32_e32 v42, 0
	v_mov_b32_e32 v44, 0
	v_add_f32_dpp v45, v32, v32 row_half_mirror row_mask:0xf bank_mask:0xf bound_ctrl:1
	s_waitcnt vmcnt(4)
	v_mul_f32_e32 v32, v143, v105
	v_fmac_f32_e32 v32, v142, v104
	v_fmac_f32_e32 v32, v144, v106
	v_fmac_f32_e32 v32, v145, v107
	v_mov_b32_e32 v46, 0
	v_mov_b32_e32 v48, 0
	v_add_f32_dpp v32, v32, v32 quad_perm:[1,0,3,2] row_mask:0xf bank_mask:0xf bound_ctrl:1
	v_mov_b32_e32 v50, 0
	v_mov_b32_e32 v52, 0
	v_add_f32_dpp v32, v32, v32 quad_perm:[2,3,0,1] row_mask:0xf bank_mask:0xf bound_ctrl:1
	v_mov_b32_e32 v37, 0
	v_mov_b32_e32 v33, 0
	v_add_f32_dpp v47, v32, v32 row_half_mirror row_mask:0xf bank_mask:0xf bound_ctrl:1
	s_waitcnt vmcnt(3)
; __device__ __forceinline__ float rowsum16(float v) { v += dppf<0xB1>(v); v += dppf<0x4E>(v); v += dppf<0x141>(v); v += dppf<0x140>(v); return v; }
; __device__ __forceinline__ void attn_sample_unit(const Params& p, int unit, float* lds) {
;     ...
;             for (int i = 0; i < 17; ++i) pr[i] = rowsum16(q0 * kv[i].x + q1 * kv[i].y + q2 * kv[i].z + q3 * kv[i].w);
; #pragma unroll
;             for (int i = 0; i < 17; ++i) {
;                 const int j = (ob * 17 + i) * 4 + ks;
;                 if (d4 == 0 && j <= 128) sbuf[j] = pr[i] - slope * (float)(j << dsh);
;             }
	v_mul_f32_e32 v32, v143, v115
	v_fmac_f32_e32 v32, v142, v114
	v_fmac_f32_e32 v32, v144, v116
	v_fmac_f32_e32 v32, v145, v117
	v_add_u32_e32 v34, s16, v175
	v_mov_b32_dpp v19, v18 row_mirror row_mask:0xf bank_mask:0xf
	v_add_f32_dpp v32, v32, v32 quad_perm:[1,0,3,2] row_mask:0xf bank_mask:0xf bound_ctrl:1
	v_mov_b32_dpp v21, v20 row_mirror row_mask:0xf bank_mask:0xf
	v_mov_b32_dpp v23, v22 row_mirror row_mask:0xf bank_mask:0xf
	v_add_f32_dpp v32, v32, v32 quad_perm:[2,3,0,1] row_mask:0xf bank_mask:0xf bound_ctrl:1
	v_mov_b32_dpp v25, v24 row_mirror row_mask:0xf bank_mask:0xf
	v_mov_b32_dpp v27, v26 row_mirror row_mask:0xf bank_mask:0xf
	v_add_f32_dpp v49, v32, v32 row_half_mirror row_mask:0xf bank_mask:0xf bound_ctrl:1
	s_waitcnt vmcnt(2)
	v_mul_f32_e32 v32, v143, v119
	v_fmac_f32_e32 v32, v142, v118
	v_fmac_f32_e32 v32, v144, v120
	v_fmac_f32_e32 v32, v145, v121
	v_mov_b32_dpp v29, v28 row_mirror row_mask:0xf bank_mask:0xf
	v_mov_b32_dpp v31, v30 row_mirror row_mask:0xf bank_mask:0xf
	v_add_f32_dpp v32, v32, v32 quad_perm:[1,0,3,2] row_mask:0xf bank_mask:0xf bound_ctrl:1
	v_mov_b32_dpp v38, v36 row_mirror row_mask:0xf bank_mask:0xf
	v_mov_b32_dpp v40, v39 row_mirror row_mask:0xf bank_mask:0xf
	v_add_f32_dpp v32, v32, v32 quad_perm:[2,3,0,1] row_mask:0xf bank_mask:0xf bound_ctrl:1
	v_mov_b32_dpp v42, v41 row_mirror row_mask:0xf bank_mask:0xf
	v_mov_b32_dpp v44, v43 row_mirror row_mask:0xf bank_mask:0xf
	v_add_f32_dpp v51, v32, v32 row_half_mirror row_mask:0xf bank_mask:0xf bound_ctrl:1
	s_waitcnt vmcnt(1)
	v_mul_f32_e32 v32, v143, v123
	v_fmac_f32_e32 v32, v142, v122
	v_fmac_f32_e32 v32, v144, v124
	v_fmac_f32_e32 v32, v145, v125
	v_mov_b32_dpp v46, v45 row_mirror row_mask:0xf bank_mask:0xf
	v_mov_b32_dpp v48, v47 row_mirror row_mask:0xf bank_mask:0xf
	v_add_f32_dpp v32, v32, v32 quad_perm:[1,0,3,2] row_mask:0xf bank_mask:0xf bound_ctrl:1
	v_mov_b32_dpp v50, v49 row_mirror row_mask:0xf bank_mask:0xf
	v_mov_b32_dpp v52, v51 row_mirror row_mask:0xf bank_mask:0xf
	v_add_f32_dpp v32, v32, v32 quad_perm:[2,3,0,1] row_mask:0xf bank_mask:0xf bound_ctrl:1
	v_lshl_add_u32 v34, v34, 2, v77
	s_nop 0
	v_add_f32_dpp v35, v32, v32 row_half_mirror row_mask:0xf bank_mask:0xf bound_ctrl:1
	s_waitcnt vmcnt(0)
	v_mul_f32_e32 v32, v143, v147
	v_fmac_f32_e32 v32, v142, v146
	v_fmac_f32_e32 v32, v144, v148
	v_fmac_f32_e32 v32, v145, v149
	v_mov_b32_dpp v37, v35 row_mirror row_mask:0xf bank_mask:0xf
	s_nop 0
	v_add_f32_dpp v32, v32, v32 quad_perm:[1,0,3,2] row_mask:0xf bank_mask:0xf bound_ctrl:1
	s_nop 1
	v_add_f32_dpp v32, v32, v32 quad_perm:[2,3,0,1] row_mask:0xf bank_mask:0xf bound_ctrl:1
	s_nop 1
	v_add_f32_dpp v32, v32, v32 row_half_mirror row_mask:0xf bank_mask:0xf bound_ctrl:1
	s_nop 1
	v_mov_b32_dpp v33, v32 row_mirror row_mask:0xf bank_mask:0xf
	s_and_saveexec_b64 s[16:17], s[6:7]
	s_cbranch_execz .LBB0_352
	v_cvt_f32_u32_e32 v1, v1
	v_cvt_f32_u32_e32 v2, v2
	v_add_f32_e32 v18, v18, v19
	v_add_f32_e32 v20, v20, v21
	v_lshl_add_u32 v0, v0, 2, v77
	v_fma_f32 v1, -v85, v1, v18
	ds_write_b32 v0, v1
	v_cvt_f32_u32_e32 v1, v3
	v_fma_f32 v2, -v85, v2, v20
	ds_write_b32 v34, v2 offset:16
	v_cvt_f32_u32_e32 v2, v4
	v_add_f32_e32 v22, v22, v23
	v_add_f32_e32 v24, v24, v25
	v_fma_f32 v1, -v85, v1, v22
	ds_write_b32 v0, v1 offset:32
	v_cvt_f32_u32_e32 v1, v5
	v_fma_f32 v2, -v85, v2, v24
	ds_write_b32 v34, v2 offset:48
	v_cvt_f32_u32_e32 v2, v6
	v_add_f32_e32 v26, v26, v27
	v_add_f32_e32 v28, v28, v29
	v_fma_f32 v1, -v85, v1, v26
	ds_write_b32 v0, v1 offset:64
	v_cvt_f32_u32_e32 v1, v7
	v_fma_f32 v2, -v85, v2, v28
	ds_write_b32 v34, v2 offset:80
	v_cvt_f32_u32_e32 v2, v8
	v_add_f32_e32 v30, v30, v31
	v_add_f32_e32 v36, v36, v38
	v_fma_f32 v1, -v85, v1, v30
	ds_write_b32 v0, v1 offset:96
	v_cvt_f32_u32_e32 v1, v9
	v_fma_f32 v2, -v85, v2, v36
	ds_write_b32 v34, v2 offset:112
	v_cvt_f32_u32_e32 v2, v10
	v_add_f32_e32 v39, v39, v40
	v_add_f32_e32 v41, v41, v42
	v_fma_f32 v1, -v85, v1, v39
	ds_write_b32 v0, v1 offset:128
	v_cvt_f32_u32_e32 v1, v12
	v_fma_f32 v2, -v85, v2, v41
	ds_write_b32 v34, v2 offset:144
	v_cvt_f32_u32_e32 v2, v13
	v_add_f32_e32 v43, v43, v44
	v_add_f32_e32 v45, v45, v46
	v_fma_f32 v1, -v85, v1, v43
	ds_write_b32 v0, v1 offset:160
	v_cvt_f32_u32_e32 v1, v15
	v_fma_f32 v2, -v85, v2, v45
	ds_write_b32 v34, v2 offset:176
	v_cvt_f32_u32_e32 v2, v16
	v_cvt_f32_u32_e32 v3, v17
	v_add_f32_e32 v47, v47, v48
	v_add_f32_e32 v49, v49, v50
	v_fma_f32 v1, -v85, v1, v47
	v_add_f32_e32 v51, v51, v52
	ds_write_b32 v0, v1 offset:192
	v_fma_f32 v1, -v85, v2, v49
	ds_write_b32 v34, v1 offset:208
	v_fma_f32 v1, -v85, v3, v51
	ds_write_b32 v0, v1 offset:224

; #define MFMA16(a, b, c) __builtin_amdgcn_mfma_f32_16x16x32_bf16((a), (b), (c), 0, 0, 0)
; template <int K>
; __device__ __forceinline__ void skinny_sample_gemm(const bfu* __restrict__ A, const bfu* __restrict__ Bt, const float* __restrict__ res, float* __restrict__ pre, float* ldsf, int bid) {
;     const int tid = threadIdx.x, lane = tid & 63, wave = __builtin_amdgcn_readfirstlane(tid >> 6), l15 = lane & 15, quad = lane >> 4;
;     const int rg = bid >> 4, cg = bid & 15;
;     constexpr int KW = K / 8, NS = KW / 32;
;     const bfu* ap = A + (size_t)(MP + rg * 16 + l15) * K + wave * KW + quad * 8;
;     const bfu* bp = Bt + (size_t)(cg * 64 + l15) * K + wave * KW + quad * 8;
;     f32x4 acc[4];
; #pragma unroll
;     for (int nt = 0; nt < 4; ++nt) acc[nt] = (f32x4){0.f, 0.f, 0.f, 0.f};
; #pragma unroll
;     for (int ks = 0; ks < NS; ++ks) {
;         const bf16x8 af = ld8g(ap + ks * 32);
; #pragma unroll
;         for (int nt = 0; nt < 4; ++nt) acc[nt] = MFMA16(af, ld8g(bp + (size_t)nt * 16 * K + ks * 32), acc[nt]);
;     }
.LBB0_1226:
	s_or_b64 exec, exec, s[0:1]
	s_add_u32 s24, s66, 0x1c00000
	v_readfirstlane_b32 s0, v172
	s_addc_u32 s25, s67, 0
	s_lshr_b32 s0, s0, 6
	s_waitcnt lgkmcnt(0)
	v_mul_u32_u24_e32 v0, 0xb00, v187
	s_mul_i32 s4, s0, 0x160
	s_mov_b32 s5, 0
	v_lshlrev_b32_e32 v44, 1, v0
	v_mov_b32_e32 v45, 0
	v_lshl_add_u64 v[4:5], s[24:25], 0, v[44:45]
	s_lshl_b64 s[4:5], s[4:5], 1
	s_movk_i32 s1, 0x1600
	v_mov_b64_e32 v[0:1], s[20:21]
	v_mad_i64_i32 v[0:1], s[6:7], v134, s1, v[0:1]
	v_lshlrev_b32_e32 v44, 1, v195
	v_lshl_add_u64 v[4:5], v[4:5], 0, s[4:5]
	v_lshl_add_u64 v[0:1], v[0:1], 0, s[4:5]
	v_lshl_add_u64 v[48:49], v[4:5], 0, v[44:45]
	s_mov_b32 s1, 0x16000
	v_lshl_add_u64 v[46:47], v[0:1], 0, v[44:45]
	v_add_co_u32_e32 v50, vcc, s1, v48
	s_barrier
	s_mov_b32 s3, 0x2c000
	v_addc_co_u32_e32 v51, vcc, 0, v49, vcc
	v_add_co_u32_e32 v52, vcc, s3, v48
	s_mov_b32 s1, 0x42000
	s_nop 1
	v_addc_co_u32_e32 v53, vcc, 0, v49, vcc
	v_add_co_u32_e32 v54, vcc, s1, v48
	s_nop 1
	v_addc_co_u32_e32 v55, vcc, 0, v49, vcc
	s_lshl_b32 s0, s0, 12
	s_add_i32 s0, s0, 0
	v_mov_b32_e32 v129, v45
	global_load_dwordx4 v[56:59], v[46:47], off
	global_load_dwordx4 v[60:63], v[48:49], off
	global_load_dwordx4 v[64:67], v[50:51], off
	global_load_dwordx4 v[68:71], v[52:53], off
	global_load_dwordx4 v[72:75], v[54:55], off
	global_load_dwordx4 v[76:79], v[46:47], off offset:64
	global_load_dwordx4 v[80:83], v[48:49], off offset:64
	global_load_dwordx4 v[84:87], v[50:51], off offset:64
	global_load_dwordx4 v[88:91], v[52:53], off offset:64
	global_load_dwordx4 v[92:95], v[54:55], off offset:64
	global_load_dwordx4 v[96:99], v[46:47], off offset:128
	global_load_dwordx4 v[100:103], v[48:49], off offset:128
	global_load_dwordx4 v[104:107], v[50:51], off offset:128
	global_load_dwordx4 v[108:111], v[52:53], off offset:128
	global_load_dwordx4 v[112:115], v[54:55], off offset:128
	global_load_dwordx4 v[116:119], v[46:47], off offset:192
	global_load_dwordx4 v[120:123], v[48:49], off offset:192
	global_load_dwordx4 v[124:127], v[50:51], off offset:192
	global_load_dwordx4 v[140:143], v[52:53], off offset:192
	global_load_dwordx4 v[144:147], v[54:55], off offset:192
	global_load_dwordx4 v[148:151], v[46:47], off offset:256
	global_load_dwordx4 v[152:155], v[48:49], off offset:256
	global_load_dwordx4 v[156:159], v[50:51], off offset:256
	global_load_dwordx4 v[160:163], v[52:53], off offset:256
	global_load_dwordx4 v[164:167], v[54:55], off offset:256
	global_load_dwordx4 v[168:171], v[46:47], off offset:320
	global_load_dwordx4 v[196:199], v[48:49], off offset:320
	global_load_dwordx4 v[200:203], v[50:51], off offset:320
	global_load_dwordx4 v[204:207], v[52:53], off offset:320
	global_load_dwordx4 v[208:211], v[54:55], off offset:320
	s_waitcnt vmcnt(25)
	v_mfma_f32_16x16x32_bf16 v[4:7], v[56:59], v[60:63], 0
	v_mfma_f32_16x16x32_bf16 v[8:11], v[56:59], v[64:67], 0
	v_mfma_f32_16x16x32_bf16 v[12:15], v[56:59], v[68:71], 0
	v_mfma_f32_16x16x32_bf16 v[0:3], v[56:59], v[72:75], 0
	global_load_dwordx4 v[56:59], v[46:47], off offset:384
	global_load_dwordx4 v[60:63], v[48:49], off offset:384
	global_load_dwordx4 v[64:67], v[50:51], off offset:384
	global_load_dwordx4 v[68:71], v[52:53], off offset:384
	global_load_dwordx4 v[72:75], v[54:55], off offset:384
	s_waitcnt vmcnt(25)
	v_mfma_f32_16x16x32_bf16 v[4:7], v[76:79], v[80:83], v[4:7]
	v_mfma_f32_16x16x32_bf16 v[8:11], v[76:79], v[84:87], v[8:11]
	v_mfma_f32_16x16x32_bf16 v[12:15], v[76:79], v[88:91], v[12:15]
	v_mfma_f32_16x16x32_bf16 v[0:3], v[76:79], v[92:95], v[0:3]
	global_load_dwordx4 v[76:79], v[46:47], off offset:448
	global_load_dwordx4 v[80:83], v[48:49], off offset:448
	global_load_dwordx4 v[84:87], v[50:51], off offset:448
	global_load_dwordx4 v[88:91], v[52:53], off offset:448
	global_load_dwordx4 v[92:95], v[54:55], off offset:448
	s_waitcnt vmcnt(25)
	v_mfma_f32_16x16x32_bf16 v[4:7], v[96:99], v[100:103], v[4:7]
	v_mfma_f32_16x16x32_bf16 v[8:11], v[96:99], v[104:107], v[8:11]
	v_mfma_f32_16x16x32_bf16 v[12:15], v[96:99], v[108:111], v[12:15]
	v_mfma_f32_16x16x32_bf16 v[0:3], v[96:99], v[112:115], v[0:3]
	global_load_dwordx4 v[96:99], v[46:47], off offset:512
	global_load_dwordx4 v[100:103], v[48:49], off offset:512
	global_load_dwordx4 v[104:107], v[50:51], off offset:512
	global_load_dwordx4 v[108:111], v[52:53], off offset:512
	global_load_dwordx4 v[112:115], v[54:55], off offset:512
	s_waitcnt vmcnt(25)
	v_mfma_f32_16x16x32_bf16 v[4:7], v[116:119], v[120:123], v[4:7]
	v_mfma_f32_16x16x32_bf16 v[8:11], v[116:119], v[124:127], v[8:11]
	v_mfma_f32_16x16x32_bf16 v[12:15], v[116:119], v[140:143], v[12:15]
	v_mfma_f32_16x16x32_bf16 v[0:3], v[116:119], v[144:147], v[0:3]
	global_load_dwordx4 v[116:119], v[46:47], off offset:576
	global_load_dwordx4 v[120:123], v[48:49], off offset:576
	global_load_dwordx4 v[124:127], v[50:51], off offset:576
	global_load_dwordx4 v[140:143], v[52:53], off offset:576
	global_load_dwordx4 v[144:147], v[54:55], off offset:576
	s_waitcnt vmcnt(25)
; __device__ __forceinline__ unsigned xb_add(unsigned* p, unsigned v) { return __hip_atomic_fetch_add(p, v, __ATOMIC_RELAXED, __HIP_MEMORY_SCOPE_AGENT); }
; #define MFMA16(a, b, c) __builtin_amdgcn_mfma_f32_16x16x32_bf16((a), (b), (c), 0, 0, 0)
; template <int K>
; __device__ __forceinline__ void skinny_sample_gemm(const bfu* __restrict__ A, const bfu* __restrict__ Bt, const float* __restrict__ res, float* __restrict__ pre, float* ldsf, int bid) {
;     ...
; #pragma unroll
;     for (int ks = 0; ks < NS; ++ks) {
;         const bf16x8 af = ld8g(ap + ks * 32);
; #pragma unroll
;         for (int nt = 0; nt < 4; ++nt) acc[nt] = MFMA16(af, ld8g(bp + (size_t)nt * 16 * K + ks * 32), acc[nt]);
;     }
; #pragma unroll
;     for (int nt = 0; nt < 4; ++nt)
; #pragma unroll
;         for (int j = 0; j < 4; ++j) ldsf[wave * 1024 + (quad * 4 + j) * 64 + nt * 16 + l15] = acc[nt][j];
;     __syncthreads();
; #pragma unroll
;     for (int i = 0; i < 2; ++i) {
;         const int e = tid + 512 * i, r = e >> 6, c = e & 63;
;         float v = 0.f;
; #pragma unroll
;         for (int w = 0; w < 8; ++w) v += ldsf[w * 1024 + e];
;         const size_t row = (size_t)(rg * 16 + r);
;         pre[(MP + row) * 1024 + cg * 64 + c] = v + ALPHA * res[row * 1024 + cg * 64 + c];
;     }
;     __syncthreads();
; }
; __device__ __forceinline__ void sample_rows_publish(unsigned* cnt_s, int bid) {
;     asm volatile("s_waitcnt vmcnt(0)" ::: "memory");
;     __syncthreads();
;     if (threadIdx.x == 0) { __builtin_amdgcn_fence(__ATOMIC_RELEASE, "agent"); asm volatile("s_waitcnt vmcnt(0)" ::: "memory"); xb_add(cnt_s + (bid >> 4) * 64, 1u); }
; }
	v_mfma_f32_16x16x32_bf16 v[4:7], v[148:151], v[152:155], v[4:7]
	v_mfma_f32_16x16x32_bf16 v[8:11], v[148:151], v[156:159], v[8:11]
	v_mfma_f32_16x16x32_bf16 v[12:15], v[148:151], v[160:163], v[12:15]
	v_mfma_f32_16x16x32_bf16 v[0:3], v[148:151], v[164:167], v[0:3]
	global_load_dwordx4 v[148:151], v[46:47], off offset:640
	global_load_dwordx4 v[152:155], v[48:49], off offset:640
	global_load_dwordx4 v[156:159], v[50:51], off offset:640
	global_load_dwordx4 v[160:163], v[52:53], off offset:640
	global_load_dwordx4 v[164:167], v[54:55], off offset:640
	s_waitcnt vmcnt(25)
	v_mfma_f32_16x16x32_bf16 v[4:7], v[168:171], v[196:199], v[4:7]
	v_mfma_f32_16x16x32_bf16 v[8:11], v[168:171], v[200:203], v[8:11]
	v_mfma_f32_16x16x32_bf16 v[12:15], v[168:171], v[204:207], v[12:15]
	v_mfma_f32_16x16x32_bf16 v[0:3], v[168:171], v[208:211], v[0:3]
	s_waitcnt vmcnt(20)
	v_mfma_f32_16x16x32_bf16 v[4:7], v[56:59], v[60:63], v[4:7]
	v_mfma_f32_16x16x32_bf16 v[8:11], v[56:59], v[64:67], v[8:11]
	v_mfma_f32_16x16x32_bf16 v[12:15], v[56:59], v[68:71], v[12:15]
	v_mfma_f32_16x16x32_bf16 v[0:3], v[56:59], v[72:75], v[0:3]
	s_waitcnt vmcnt(15)
	v_mfma_f32_16x16x32_bf16 v[4:7], v[76:79], v[80:83], v[4:7]
	v_mfma_f32_16x16x32_bf16 v[8:11], v[76:79], v[84:87], v[8:11]
	v_mfma_f32_16x16x32_bf16 v[12:15], v[76:79], v[88:91], v[12:15]
	v_mfma_f32_16x16x32_bf16 v[0:3], v[76:79], v[92:95], v[0:3]
	s_waitcnt vmcnt(10)
	v_mfma_f32_16x16x32_bf16 v[4:7], v[96:99], v[100:103], v[4:7]
	v_mfma_f32_16x16x32_bf16 v[8:11], v[96:99], v[104:107], v[8:11]
	v_mfma_f32_16x16x32_bf16 v[12:15], v[96:99], v[108:111], v[12:15]
	v_mfma_f32_16x16x32_bf16 v[0:3], v[96:99], v[112:115], v[0:3]
	s_waitcnt vmcnt(5)
	v_mfma_f32_16x16x32_bf16 v[4:7], v[116:119], v[120:123], v[4:7]
	v_mfma_f32_16x16x32_bf16 v[8:11], v[116:119], v[124:127], v[8:11]
	v_mfma_f32_16x16x32_bf16 v[12:15], v[116:119], v[140:143], v[12:15]
	v_mfma_f32_16x16x32_bf16 v[0:3], v[116:119], v[144:147], v[0:3]
	s_waitcnt vmcnt(0)
	v_mfma_f32_16x16x32_bf16 v[4:7], v[148:151], v[152:155], v[4:7]
	v_mfma_f32_16x16x32_bf16 v[8:11], v[148:151], v[156:159], v[8:11]
	v_mfma_f32_16x16x32_bf16 v[12:15], v[148:151], v[160:163], v[12:15]
	v_mfma_f32_16x16x32_bf16 v[0:3], v[148:151], v[164:167], v[0:3]
	v_add3_u32 v24, s0, v135, v186
	s_add_u32 s0, s66, s10
	s_addc_u32 s1, s67, 0
	s_add_u32 s3, s66, 0x38a0d000
	s_addc_u32 s33, s67, 0
	s_nop 7
	ds_write2_b32 v24, v4, v8 offset1:16
	ds_write2_b32 v24, v5, v9 offset0:64 offset1:80
	ds_write2_b32 v24, v6, v10 offset0:128 offset1:144
	ds_write2_b32 v24, v7, v11 offset0:192 offset1:208
	ds_write2_b32 v24, v12, v0 offset0:32 offset1:48
	ds_write2_b32 v24, v13, v1 offset0:96 offset1:112
	ds_write2_b32 v24, v14, v2 offset0:160 offset1:176
	ds_write2_b32 v24, v15, v3 offset0:224 offset1:240
	v_lshl_add_u64 v[0:1], s[0:1], 0, v[128:129]
	s_mov_b64 s[0:1], 0x30e00000
	v_lshl_add_u64 v[0:1], v[0:1], 0, s[0:1]
	v_lshl_add_u64 v[2:3], v[0:1], 0, v[130:131]
	s_waitcnt lgkmcnt(0)
	s_barrier
	v_lshl_add_u64 v[0:1], v[0:1], 0, v[132:133]
	global_load_dword v16, v[2:3], off
	global_load_dword v17, v[0:1], off
	ds_read2st64_b32 v[0:1], v173 offset1:8
	ds_read2st64_b32 v[2:3], v173 offset0:16 offset1:24
	ds_read2st64_b32 v[4:5], v173 offset0:32 offset1:40
	ds_read2st64_b32 v[6:7], v173 offset0:48 offset1:56
	ds_read2st64_b32 v[8:9], v173 offset0:64 offset1:72
	ds_read2st64_b32 v[10:11], v173 offset0:80 offset1:88
	ds_read2st64_b32 v[12:13], v173 offset0:96 offset1:104
	ds_read2st64_b32 v[14:15], v173 offset0:112 offset1:120
	s_waitcnt lgkmcnt(7)
	v_add_f32_e32 v0, 0, v0
	v_add_f32_e32 v1, 0, v1
	s_waitcnt lgkmcnt(6)
	v_add_f32_e32 v0, v0, v2
	v_add_f32_e32 v1, v1, v3
	s_waitcnt lgkmcnt(5)
	v_add_f32_e32 v0, v0, v4
	v_add_f32_e32 v1, v1, v5
	s_waitcnt lgkmcnt(4)
	v_add_f32_e32 v0, v0, v6
	v_add_f32_e32 v1, v1, v7
	s_waitcnt lgkmcnt(3)
	v_add_f32_e32 v0, v0, v8
	v_add_f32_e32 v1, v1, v9
	s_waitcnt lgkmcnt(2)
	v_add_f32_e32 v0, v0, v10
	v_add_f32_e32 v1, v1, v11
	s_waitcnt lgkmcnt(1)
	v_add_f32_e32 v0, v0, v12
	v_add_f32_e32 v1, v1, v13
	s_waitcnt lgkmcnt(0)
	v_add_f32_e32 v0, v0, v14
	v_add_f32_e32 v1, v1, v15
	s_waitcnt vmcnt(1)
	v_fmac_f32_e32 v0, 0x3f9837f0, v16
	s_waitcnt vmcnt(0)
	v_fmac_f32_e32 v1, 0x3f9837f0, v17
	global_store_dword v[136:137], v0, off
	global_store_dword v[138:139], v1, off
	s_barrier
	s_waitcnt vmcnt(0)
	s_barrier
	s_mov_b64 s[0:1], exec
	v_readlane_b32 s4, v252, 6
	v_readlane_b32 s5, v252, 7
	s_and_b64 s[4:5], s[0:1], s[4:5]
	s_mov_b64 exec, s[4:5]
	s_cbranch_execz .LBB0_1229
	s_mov_b64 s[4:5], exec
	v_mbcnt_lo_u32_b32 v0, s4, 0
	buffer_wbl2 sc1
	s_waitcnt vmcnt(0)
	s_waitcnt vmcnt(0)
	v_mbcnt_hi_u32_b32 v0, s5, v0
	v_cmp_eq_u32_e32 vcc, 0, v0
	s_and_b64 s[6:7], exec, vcc
	s_mov_b64 exec, s[6:7]
	s_cbranch_execz .LBB0_1229
	s_lshl_b32 s6, s2, 2
	s_andn2_b32 s6, s6, 63
	s_ashr_i32 s7, s6, 31
	s_lshl_b64 s[6:7], s[6:7], 2
	s_add_u32 s6, s3, s6
	s_addc_u32 s7, s33, s7
	s_bcnt1_i32_b64 s4, s[4:5]
	v_mov_b32_e32 v0, 0
	v_mov_b32_e32 v1, s4
	global_atomic_add v0, v1, s[6:7]
